# scan state layout with 16 contiguous columns per lane: a/wr operands as 2 ds_read_b128 (2 fewer LDS reads per step)
# baseline (speedup 1.0000x reference)
; DI void scan_item(const Params& p, char* smem, int b, int h, bool prompt, const int g_wave) {
;     ...
;     const int li = lane & 15, g = lane >> 4, irow = wid * 16 + li;
;     f32x2 S0[4], S1[4];
;     if (prompt) { for (int e = 0; e < 4; ++e) { S0[e] = (f32x2){0.f, 0.f}; S1[e] = (f32x2){0.f, 0.f}; } }
;     else {
;       const float* s0 = p.state_wkv + ((size_t)(b * 16 + h) * 64 + irow) * 64 + 8 * g;
;       for (int e = 0; e < 4; ++e) { S0[e] = (f32x2){s0[2 * e], s0[2 * e + 1]}; S1[e] = (f32x2){s0[32 + 2 * e], s0[32 + 2 * e + 1]}; }
;     }
;     const int abf_off = ((lane & 3) == 1 ? 12288 : 8192) + 16 * g;
;     __syncthreads();
; #pragma unroll 1
;     for (int k = 0; k < nch; ++k) {
;       const char* set = smem + (k & 1) * SETB;
;       const float* bW = (const float*)set + 8 * g;
;       const char* bA = set + abf_off;
;       const float* bV = (const float*)(set + 40960) + irow;
;       float* Yp = (float*)(set + 49152) + irow;
;       const float2* BK = (const float2*)(set + 57472);
;     ...
;       f32x4v Pw0, Pw1, Pw2, Pw3, Pb0, Pb1, Pb2, Pb3, Pk0, Pk1, Pk2, Pk3; bf16x8 Pa0, Pa1; float Pv; float2 Ps;
;       f32x4v Qw0, Qw1, Qw2, Qw3, Qb0, Qb1, Qb2, Qb3, Qk0, Qk1, Qk2, Qk3; bf16x8 Qa0, Qa1; float Qv; float2 Qs;
;       LOADV(P, 0);
; #pragma unroll 1
;       for (int t = 0; t < 32; t += 2) {
;         LOADV(Q, t + 1);
;         STEP(P, t);
;         LOADV(P, t + 2);
;         STEP(Q, t + 1);
;       }
;     ...
;       asm volatile("s_waitcnt lgkmcnt(0)" ::: "memory");
;       __builtin_amdgcn_s_barrier();
;       asm volatile("" ::: "memory");
;     }
;     float* so = p.out + (prompt ? O_WKVP : O_WKVS) + ((size_t)(b * 16 + h) * 64 + irow) * 64 + 8 * g;
;     *(float4*)so = make_float4(S0[0].x, S0[0].y, S0[1].x, S0[1].y); *(float4*)(so + 4) = make_float4(S0[2].x, S0[2].y, S0[3].x, S0[3].y);
;     *(float4*)(so + 32) = make_float4(S1[0].x, S1[0].y, S1[1].x, S1[1].y); *(float4*)(so + 36) = make_float4(S1[2].x, S1[2].y, S1[3].x, S1[3].y);
.LBB0_791:
	s_and_b64 vcc, exec, s[4:5]
	s_cbranch_vccz .LBB0_680
	v_and_b32_e32 v20, 15, v119
	v_readlane_b32 s0, v255, 9
	v_and_b32_e32 v82, 48, v119
	v_mov_b32_e32 v4, 0
	v_or_b32_e32 v79, s0, v20
	s_andn2_b64 vcc, exec, s[40:41]
	v_lshlrev_b32_e32 v2, 8, v79
	v_lshlrev_b32_e32 v76, 2, v82
	v_mov_b32_e32 v5, 0
	v_mov_b32_e32 v6, 0
	v_mov_b32_e32 v7, 0
	v_mov_b32_e32 v8, 0
	v_mov_b32_e32 v9, 0
	v_mov_b32_e32 v10, 0
	v_mov_b32_e32 v11, 0
	v_mov_b32_e32 v16, 0
	v_mov_b32_e32 v17, 0
	v_mov_b32_e32 v18, 0
	v_mov_b32_e32 v19, 0
	v_mov_b32_e32 v12, 0
	v_mov_b32_e32 v13, 0
	v_mov_b32_e32 v14, 0
	v_mov_b32_e32 v15, 0
	s_cbranch_vccnz .LBB0_794
	s_ashr_i32 s51, s50, 31
	s_lshl_b64 s[0:1], s[50:51], 14
	s_add_u32 s0, s20, s0
	s_addc_u32 s1, s21, s1
	v_lshl_add_u64 v[4:5], s[0:1], 0, v[2:3]
	v_mov_b32_e32 v77, v3
	v_lshl_add_u64 v[8:9], v[4:5], 0, v[76:77]
	global_load_dwordx4 v[16:19], v[8:9], off
	global_load_dwordx4 v[12:15], v[8:9], off offset:16
	global_load_dwordx4 v[4:7], v[8:9], off offset:32
	s_nop 0
	global_load_dwordx4 v[8:11], v[8:9], off offset:48
.LBB0_794:
	v_and_b32_e32 v21, 3, v119
	v_mov_b32_e32 v22, 0x2000
	v_mov_b32_e32 v23, 0x3000
	v_cmp_eq_u32_e32 vcc, 1, v21
	v_lshlrev_b32_e32 v83, 2, v21
	v_lshlrev_b32_e32 v21, 1, v82
	v_cndmask_b32_e32 v77, v22, v23, vcc
	v_add_u32_e32 v77, v77, v21
	v_mov_b32_e32 v22, 0x4000
	v_add3_u32 v83, v83, v76, v22
	v_add_u32_e32 v27, 0x2000, v83
	v_lshlrev_b32_e32 v84, 2, v79
	v_add_u32_e32 v84, 0xa000, v84
	v_mov_b32_e32 v85, v76
	s_mov_b32 s0, 0
	s_waitcnt vmcnt(0)
	s_barrier
.LBB0_795:
	s_bitcmp1_b32 s0, 0
	s_cselect_b32 s4, 0xe180, 0
	s_add_i32 s1, s4, 16
	v_add_u32_e32 v88, s1, v85
	v_add_u32_e32 v86, s1, v83
	v_add_u32_e32 v26, s1, v27
	v_add_u32_e32 v89, s1, v77
	v_add_u32_e32 v87, s1, v84
	s_add_i32 s1, s1, 0xe080
	v_mov_b32_e32 v111, s1
	ds_read_b128 v[52:55], v88
	ds_read_b128 v[40:43], v88 offset:16
	ds_read_b128 v[28:31], v88 offset:32
	ds_read_b128 v[20:23], v88 offset:48
	ds_read2_b32 v[60:61], v86 offset0:0 offset1:4
	ds_read2_b32 v[62:63], v86 offset0:8 offset1:12
	ds_read2_b32 v[32:33], v26 offset0:0 offset1:4
	ds_read2_b32 v[34:35], v26 offset0:8 offset1:12
	ds_read_b128 v[72:75], v89
	ds_read_b128 v[68:71], v89 offset:16
	ds_read_b32 v78, v87
	ds_read_b64 v[80:81], v111
	s_mov_b32 s4, -2
.LBB0_796:
	ds_read_b128 v[90:93], v88 offset:256
	ds_read_b128 v[94:97], v88 offset:272
	ds_read_b128 v[98:101], v88 offset:288
	ds_read_b128 v[102:105], v88 offset:304
	ds_read2_b32 v[106:107], v86 offset0:64 offset1:68
	ds_read2_b32 v[108:109], v86 offset0:72 offset1:76
	ds_read2_b32 v[36:37], v26 offset0:64 offset1:68
	ds_read2_b32 v[38:39], v26 offset0:72 offset1:76
	ds_read_b128 v[138:141], v89 offset:128
	ds_read_b128 v[142:145], v89 offset:144
	ds_read_b32 v154, v87 offset:256
	ds_read_b64 v[156:157], v111 offset:8
	v_cvt_pk_bf16_f32 v146, v16, v17
	v_cvt_pk_bf16_f32 v147, v18, v19
	v_cvt_pk_bf16_f32 v148, v12, v13
	v_cvt_pk_bf16_f32 v149, v14, v15
	v_cvt_pk_bf16_f32 v150, v4, v5
	v_cvt_pk_bf16_f32 v151, v6, v7
	v_cvt_pk_bf16_f32 v152, v8, v9
	v_cvt_pk_bf16_f32 v153, v10, v11
	s_waitcnt lgkmcnt(12)
	v_mfma_f32_16x16x32_bf16 v[72:75], v[72:75], v[146:149], 0
	v_mfma_f32_16x16x32_bf16 v[68:71], v[68:71], v[150:153], v[72:75]
	v_pk_mul_f32 v[16:17], v[16:17], v[52:53]
	v_pk_mul_f32 v[18:19], v[18:19], v[54:55]
	v_pk_mul_f32 v[12:13], v[12:13], v[40:41]
	v_pk_mul_f32 v[14:15], v[14:15], v[42:43]
	v_pk_mul_f32 v[4:5], v[4:5], v[28:29]
	v_pk_mul_f32 v[6:7], v[6:7], v[30:31]
	v_pk_mul_f32 v[8:9], v[8:9], v[20:21]
	v_pk_mul_f32 v[10:11], v[10:11], v[22:23]
	v_mfma_f32_4x4x1_16b_f32 v[16:19], v32, v78, v[16:19]
	v_mfma_f32_4x4x1_16b_f32 v[12:15], v33, v78, v[12:15]
	v_mfma_f32_4x4x1_16b_f32 v[4:7], v34, v78, v[4:7]
	v_mfma_f32_4x4x1_16b_f32 v[8:11], v35, v78, v[8:11]
	v_fma_f32 v146, v78, v81, v69
	v_fmac_f32_e32 v146, v68, v80
	v_mfma_f32_4x4x1_16b_f32 v[16:19], v60, v68, v[16:19]
	v_mfma_f32_4x4x1_16b_f32 v[12:15], v61, v68, v[12:15]
	v_mfma_f32_4x4x1_16b_f32 v[4:7], v62, v68, v[4:7]
	v_mfma_f32_4x4x1_16b_f32 v[8:11], v63, v68, v[8:11]
	ds_write_b32 v87, v146 offset:8192
	ds_read_b128 v[52:55], v88 offset:512
	ds_read_b128 v[40:43], v88 offset:528
	ds_read_b128 v[28:31], v88 offset:544
	ds_read_b128 v[20:23], v88 offset:560
	ds_read2_b32 v[60:61], v86 offset0:128 offset1:132
	ds_read2_b32 v[62:63], v86 offset0:136 offset1:140
	ds_read2_b32 v[32:33], v26 offset0:128 offset1:132
	ds_read2_b32 v[34:35], v26 offset0:136 offset1:140
	ds_read_b128 v[72:75], v89 offset:256
	ds_read_b128 v[68:71], v89 offset:272
	ds_read_b32 v78, v87 offset:512
	ds_read_b64 v[80:81], v111 offset:16
	v_cvt_pk_bf16_f32 v146, v16, v17
	v_cvt_pk_bf16_f32 v147, v18, v19
	v_cvt_pk_bf16_f32 v148, v12, v13
	v_cvt_pk_bf16_f32 v149, v14, v15
	v_cvt_pk_bf16_f32 v150, v4, v5
	v_cvt_pk_bf16_f32 v151, v6, v7
	v_cvt_pk_bf16_f32 v152, v8, v9
	v_cvt_pk_bf16_f32 v153, v10, v11
	s_waitcnt lgkmcnt(12)
	v_mfma_f32_16x16x32_bf16 v[138:141], v[138:141], v[146:149], 0
	v_mfma_f32_16x16x32_bf16 v[142:145], v[142:145], v[150:153], v[138:141]
	v_pk_mul_f32 v[16:17], v[16:17], v[90:91]
	v_pk_mul_f32 v[18:19], v[18:19], v[92:93]
	v_pk_mul_f32 v[12:13], v[12:13], v[94:95]
	v_pk_mul_f32 v[14:15], v[14:15], v[96:97]
	v_pk_mul_f32 v[4:5], v[4:5], v[98:99]
	v_pk_mul_f32 v[6:7], v[6:7], v[100:101]
	v_pk_mul_f32 v[8:9], v[8:9], v[102:103]
	v_pk_mul_f32 v[10:11], v[10:11], v[104:105]
	v_mfma_f32_4x4x1_16b_f32 v[16:19], v36, v154, v[16:19]
	v_mfma_f32_4x4x1_16b_f32 v[12:15], v37, v154, v[12:15]
	v_mfma_f32_4x4x1_16b_f32 v[4:7], v38, v154, v[4:7]
	v_mfma_f32_4x4x1_16b_f32 v[8:11], v39, v154, v[8:11]
	v_fma_f32 v146, v154, v157, v143
	v_fmac_f32_e32 v146, v142, v156
	v_mfma_f32_4x4x1_16b_f32 v[16:19], v106, v142, v[16:19]
	v_mfma_f32_4x4x1_16b_f32 v[12:15], v107, v142, v[12:15]
	v_mfma_f32_4x4x1_16b_f32 v[4:7], v108, v142, v[4:7]
	v_mfma_f32_4x4x1_16b_f32 v[8:11], v109, v142, v[8:11]
	ds_write_b32 v87, v146 offset:8448
	s_add_i32 s4, s4, 2
	v_add_u32_e32 v88, 0x200, v88
	v_add_u32_e32 v86, 0x200, v86
	v_add_u32_e32 v26, 0x200, v26
	v_add_u32_e32 v89, 0x100, v89
	v_add_u32_e32 v87, 0x200, v87
	v_add_u32_e32 v111, 16, v111
	s_cmp_gt_u32 s4, 29
	s_cbranch_scc0 .LBB0_796
	s_waitcnt lgkmcnt(0)
	s_barrier
	s_add_i32 s0, s0, 1
	s_cmp_eq_u32 s0, s43
	s_cbranch_scc0 .LBB0_795
	s_and_b64 s[0:1], s[38:39], exec
	s_mov_b32 s0, 0x30200000
	s_cselect_b32 s0, s0, 0x30819000
	s_add_u32 s4, s70, s0
	s_addc_u32 s5, s71, 0
	s_ashr_i32 s43, s42, 31
	s_lshl_b64 s[0:1], s[42:43], 14
	s_add_u32 s0, s4, s0
	s_addc_u32 s1, s5, s1
	s_nop 7
	s_nop 3
	v_lshl_add_u64 v[20:21], s[0:1], 0, v[2:3]
	v_mov_b32_e32 v77, v3
	v_lshl_add_u64 v[20:21], v[20:21], 0, v[76:77]
	global_store_dwordx4 v[20:21], v[16:19], off
	global_store_dwordx4 v[20:21], v[12:15], off offset:16
	global_store_dwordx4 v[20:21], v[4:7], off offset:32
	global_store_dwordx4 v[20:21], v[8:11], off offset:48
	s_branch .LBB0_680
